# SSD scan no longer rewrites S for the two-chunk sequences (entering state = partner chunk local state or zero); y phase reads the partner chunk with a zero mask
# speedup vs baseline: 1.0159x; 1.0159x over previous
.LBB0_2044:
	s_andn2_saveexec_b64 s[12:13], s[12:13]
	s_cbranch_execz .LBB0_2041
	v_lshlrev_b32_e32 v11, 1, v14
	v_readlane_b32 s16, v252, 49
	v_lshlrev_b32_e32 v128, 8, v75
	v_readlane_b32 s17, v252, 50
	v_or_b32_e32 v6, v16, v11
	v_mov_b32_e32 v1, v129
	v_lshl_add_u64 v[2:3], s[16:17], 0, v[128:129]
	v_ashrrev_i32_e32 v7, 31, v6
	v_lshl_add_u64 v[4:5], v[2:3], 0, v[0:1]
	v_lshlrev_b64 v[0:1], 20, v[6:7]
	v_lshlrev_b32_e32 v6, 6, v6
	v_or_b32_e32 v13, v65, v64
	v_or3_b32 v6, v6, v64, v65
	v_lshlrev_b32_e32 v128, 14, v13
	v_lshl_add_u64 v[22:23], v[4:5], 0, v[0:1]
	v_ashrrev_i32_e32 v7, 31, v6
	v_mov_b32_e32 v9, v129
	v_lshl_add_u64 v[0:1], v[22:23], 0, v[128:129]
	v_lshl_add_u64 v[6:7], v[6:7], 2, s[4:5]
	global_load_dwordx4 v[0:3], v[0:1], off
	v_bitop3_b32 v18, v16, 1, v11 bitop3:0x36
	global_load_dword v13, v[6:7], off
	v_ashrrev_i32_e32 v19, 31, v18
	v_lshlrev_b64 v[6:7], 20, v[18:19]
	v_lshlrev_b32_e32 v11, 6, v18
	v_lshl_add_u64 v[24:25], v[4:5], 0, v[6:7]
	v_or3_b32 v18, v11, v64, v65
	v_lshl_add_u64 v[4:5], v[24:25], 0, v[128:129]
	v_ashrrev_i32_e32 v19, 31, v18
	global_load_dwordx4 v[4:7], v[4:5], off
	v_lshl_add_u64 v[18:19], v[18:19], 2, s[4:5]
	global_load_dword v26, v[18:19], off
	v_lshlrev_b32_e32 v11, 14, v64
	v_cvt_pk_bf16_f32 v18, v9, v9
	v_lshl_or_b32 v128, v16, 19, v11
	v_ashrrev_i32_e32 v15, 31, v14
	v_mov_b32_e32 v19, v18
	v_mov_b32_e32 v20, v18
	v_mov_b32_e32 v21, v18
	v_lshl_add_u64 v[22:23], v[22:23], 0, v[128:129]
	v_lshlrev_b64 v[14:15], 2, v[14:15]
	v_lshl_add_u64 v[24:25], v[24:25], 0, v[128:129]
	v_mov_b32_e32 v11, v129
	s_waitcnt vmcnt(3)
	v_lshlrev_b32_e32 v20, 16, v0
	v_and_b32_e32 v21, 0xffff0000, v0
	s_waitcnt vmcnt(2)
	v_mul_f32_e32 v18, v9, v13
	v_lshlrev_b32_e32 v0, 16, v1
	v_and_b32_e32 v1, 0xffff0000, v1
	v_or_b32_e32 v9, v14, v16
	v_pk_add_f32 v[22:23], v[18:19], v[0:1] op_sel_hi:[0,1]
	v_lshlrev_b32_e32 v0, 16, v2
	v_and_b32_e32 v1, 0xffff0000, v2
	v_or_b32_e32 v14, s14, v9
	v_pk_add_f32 v[28:29], v[18:19], v[0:1] op_sel_hi:[0,1]
	v_lshlrev_b32_e32 v0, 16, v3
	v_and_b32_e32 v1, 0xffff0000, v3
	v_lshlrev_b64 v[14:15], 20, v[14:15]
	v_pk_add_f32 v[20:21], v[18:19], v[20:21] op_sel_hi:[0,1]
	v_pk_add_f32 v[18:19], v[18:19], v[0:1] op_sel_hi:[0,1]
	v_lshl_add_u64 v[14:15], s[6:7], 0, v[14:15]
	v_mov_b32_e32 v13, v129
	v_cvt_pk_bf16_f32 v0, v20, v21
	v_cvt_pk_bf16_f32 v1, v22, v23
	v_cvt_pk_bf16_f32 v2, v28, v29
	v_cvt_pk_bf16_f32 v3, v18, v19
	v_lshl_add_u64 v[12:13], v[14:15], 0, v[12:13]
	v_lshl_add_u64 v[10:11], v[12:13], 0, v[10:11]
	v_mov_b32_e32 v9, v129
	s_waitcnt vmcnt(1)
	v_lshlrev_b32_e32 v0, 16, v4
	v_and_b32_e32 v1, 0xffff0000, v4
	v_lshlrev_b32_e32 v2, 16, v5
	v_and_b32_e32 v3, 0xffff0000, v5
	s_waitcnt vmcnt(0)
	v_pk_fma_f32 v[0:1], v[26:27], v[20:21], v[0:1] op_sel_hi:[0,1,1]
	v_pk_fma_f32 v[2:3], v[26:27], v[22:23], v[2:3] op_sel_hi:[0,1,1]
	v_lshlrev_b32_e32 v4, 16, v6
	v_and_b32_e32 v5, 0xffff0000, v6
	v_lshlrev_b32_e32 v6, 16, v7
	v_and_b32_e32 v7, 0xffff0000, v7
	v_lshl_add_u64 v[8:9], v[10:11], 0, v[8:9]
	v_pk_fma_f32 v[4:5], v[26:27], v[28:29], v[4:5] op_sel_hi:[0,1,1]
	v_pk_fma_f32 v[6:7], v[26:27], v[18:19], v[6:7] op_sel_hi:[0,1,1]
	global_store_dwordx4 v[8:9], v[0:3], off nt
	global_store_dwordx4 v[8:9], v[4:7], off offset:16 nt
	s_branch .LBB0_2041

.LBB0_2101:
	s_ashr_i32 s12, s13, 3
	s_lshl_b32 s14, s12, 7
	v_add_u32_e32 v0, s14, v170
	v_ashrrev_i32_e32 v1, 31, v0
	v_readlane_b32 s16, v252, 47
	v_writelane_b32 v255, s13, 49
	s_and_b32 s13, s13, 7
	v_lshlrev_b64 v[0:1], 11, v[0:1]
	v_readlane_b32 s17, v252, 48
	v_readlane_b32 s22, v252, 12
	v_readlane_b32 s23, v252, 13
	v_lshl_add_u64 v[0:1], s[16:17], 0, v[0:1]
	s_lshl_b32 s22, s13, 8
	v_lshl_add_u64 v[0:1], v[0:1], 0, s[22:23]
	v_lshlrev_b32_e32 v2, 1, v172
	v_mov_b32_e32 v3, v129
	v_lshl_add_u64 v[0:1], v[0:1], 0, v[2:3]
	global_load_dwordx4 v[130:133], v[0:1], off
	global_load_dwordx4 v[134:137], v[0:1], off offset:32
	global_load_dwordx4 v[138:141], v[0:1], off offset:64
	global_load_dwordx4 v[142:145], v[0:1], off offset:96
	global_load_dwordx4 v[146:149], v[0:1], off offset:128
	global_load_dwordx4 v[150:153], v[0:1], off offset:160
	global_load_dwordx4 v[154:157], v[0:1], off offset:192
	global_load_dwordx4 v[158:161], v[0:1], off offset:224
	v_or_b32_e32 v0, s14, v173
	v_ashrrev_i32_e32 v1, 31, v0
	v_readlane_b32 s16, v252, 45
	v_lshlrev_b64 v[0:1], 11, v[0:1]
	v_readlane_b32 s17, v252, 46
	s_mov_b32 s15, 0x10000
	s_lshl_b32 s13, s13, 2
	v_lshl_add_u64 v[0:1], s[16:17], 0, v[0:1]
	v_lshl_add_u64 v[0:1], v[0:1], 0, s[22:23]
	v_lshl_add_u64 v[64:65], v[0:1], 0, v[2:3]
	v_add_co_u32_e32 v66, vcc, s15, v64
	s_mov_b32 s15, 0x20000
	s_nop 0
	v_addc_co_u32_e32 v67, vcc, 0, v65, vcc
	v_add_co_u32_e32 v68, vcc, s15, v64
	s_mov_b32 s15, 0x30000
	s_nop 0
	v_addc_co_u32_e32 v69, vcc, 0, v65, vcc
	v_add_co_u32_e32 v70, vcc, s15, v64
	v_writelane_b32 v255, s13, 50
	s_nop 0
	v_addc_co_u32_e32 v71, vcc, 0, v65, vcc
	s_ashr_i32 s13, s12, 31
	s_lshl_b64 s[20:21], s[12:13], 19
	v_readlane_b32 s16, v252, 43
	s_add_u32 s15, s16, s20
	v_writelane_b32 v255, s15, 51
	v_readlane_b32 s17, v252, 44
	v_writelane_b32 v255, s20, 52
	s_addc_u32 s15, s17, s21
	s_lshl_b64 s[16:17], s[12:13], 20
	v_writelane_b32 v255, s21, 53
	v_readlane_b32 s20, v252, 49
	v_writelane_b32 v255, s15, 54
	v_readlane_b32 s21, v252, 50
	s_add_u32 s15, s20, s16
	v_writelane_b32 v255, s15, 55
	s_addc_u32 s15, s21, s17
	v_writelane_b32 v255, s15, 56
	s_cmp_lt_u32 s12, 64
	s_cselect_b32 s15, 1, 0
	s_xor_b32 s16, s12, s15
	s_mov_b32 s17, 0
	s_lshl_b64 s[20:21], s[16:17], 19
	v_writelane_b32 v255, s20, 52
	v_writelane_b32 v255, s21, 53
	s_lshl_b64 s[16:17], s[16:17], 20
	v_readlane_b32 s20, v252, 49
	v_readlane_b32 s21, v252, 50
	s_add_u32 s20, s20, s16
	s_addc_u32 s21, s21, s17
	v_writelane_b32 v255, s20, 55
	v_writelane_b32 v255, s21, 56
	s_and_b32 s16, s12, 1
	s_xor_b32 s17, s16, 1
	s_and_b32 s17, s17, s15
	s_and_b32 s16, s16, s15
	s_add_i32 s17, s17, -1
	s_add_i32 s16, s16, -1
	v_writelane_b32 v255, s17, 58
	v_writelane_b32 v255, s16, 59
	s_mov_b32 s19, 0
	s_lshl_b64 s[12:13], s[12:13], 13
	global_load_dwordx4 v[76:79], v[64:65], off
	global_load_dwordx4 v[80:83], v[66:67], off
	global_load_dwordx4 v[84:87], v[68:69], off
	global_load_dwordx4 v[88:91], v[70:71], off
	global_load_dwordx4 v[92:95], v[64:65], off offset:32
	global_load_dwordx4 v[96:99], v[66:67], off offset:32
	global_load_dwordx4 v[100:103], v[68:69], off offset:32
	global_load_dwordx4 v[104:107], v[70:71], off offset:32
	global_load_dwordx4 v[108:111], v[64:65], off offset:64
	global_load_dwordx4 v[112:115], v[66:67], off offset:64
	global_load_dwordx4 v[116:119], v[68:69], off offset:64
	global_load_dwordx4 v[120:123], v[70:71], off offset:64
	global_load_dwordx4 v[124:127], v[64:65], off offset:96
	global_load_dwordx4 v[72:75], v[66:67], off offset:96
	global_load_dwordx4 v[212:215], v[68:69], off offset:96
	global_load_dwordx4 v[222:225], v[70:71], off offset:96
	global_load_dwordx4 v[234:237], v[64:65], off offset:128
	global_load_dwordx4 v[238:241], v[66:67], off offset:128
	global_load_dwordx4 v[242:245], v[68:69], off offset:128
	global_load_dwordx4 v[246:249], v[70:71], off offset:128
	s_waitcnt vmcnt(19)
	v_mfma_f32_32x32x16_bf16 v[0:15], v[76:79], v[130:133], 0
	global_load_dwordx4 v[76:79], v[64:65], off offset:160
	s_waitcnt vmcnt(19)
	v_mfma_f32_32x32x16_bf16 v[16:31], v[80:83], v[130:133], 0
	global_load_dwordx4 v[80:83], v[66:67], off offset:160
	s_waitcnt vmcnt(19)
	v_mfma_f32_32x32x16_bf16 v[32:47], v[84:87], v[130:133], 0
	global_load_dwordx4 v[84:87], v[68:69], off offset:160
	s_waitcnt vmcnt(19)
	v_mfma_f32_32x32x16_bf16 v[48:63], v[88:91], v[130:133], 0
	global_load_dwordx4 v[88:91], v[70:71], off offset:160
	s_waitcnt vmcnt(19)
	v_mfma_f32_32x32x16_bf16 v[0:15], v[92:95], v[134:137], v[0:15]
	global_load_dwordx4 v[92:95], v[64:65], off offset:192
	s_waitcnt vmcnt(19)
	v_mfma_f32_32x32x16_bf16 v[16:31], v[96:99], v[134:137], v[16:31]
	global_load_dwordx4 v[96:99], v[66:67], off offset:192
	s_waitcnt vmcnt(19)
	v_mfma_f32_32x32x16_bf16 v[32:47], v[100:103], v[134:137], v[32:47]
	global_load_dwordx4 v[100:103], v[68:69], off offset:192
	s_waitcnt vmcnt(19)
	v_mfma_f32_32x32x16_bf16 v[48:63], v[104:107], v[134:137], v[48:63]
	global_load_dwordx4 v[104:107], v[70:71], off offset:192
	s_waitcnt vmcnt(19)
	v_mfma_f32_32x32x16_bf16 v[0:15], v[108:111], v[138:141], v[0:15]
	global_load_dwordx4 v[108:111], v[64:65], off offset:224
	s_waitcnt vmcnt(19)
	v_mfma_f32_32x32x16_bf16 v[16:31], v[112:115], v[138:141], v[16:31]
	global_load_dwordx4 v[112:115], v[66:67], off offset:224
	s_waitcnt vmcnt(19)
	v_mfma_f32_32x32x16_bf16 v[32:47], v[116:119], v[138:141], v[32:47]
	global_load_dwordx4 v[116:119], v[68:69], off offset:224
	s_waitcnt vmcnt(19)
	v_mfma_f32_32x32x16_bf16 v[48:63], v[120:123], v[138:141], v[48:63]
	global_load_dwordx4 v[120:123], v[70:71], off offset:224
	s_waitcnt vmcnt(19)
	v_mfma_f32_32x32x16_bf16 v[0:15], v[124:127], v[142:145], v[0:15]
	s_waitcnt vmcnt(18)
	v_mfma_f32_32x32x16_bf16 v[16:31], v[72:75], v[142:145], v[16:31]
	s_waitcnt vmcnt(17)
	v_mfma_f32_32x32x16_bf16 v[32:47], v[212:215], v[142:145], v[32:47]
	s_waitcnt vmcnt(16)
	v_mfma_f32_32x32x16_bf16 v[48:63], v[222:225], v[142:145], v[48:63]
	s_waitcnt vmcnt(15)
	v_mfma_f32_32x32x16_bf16 v[0:15], v[234:237], v[146:149], v[0:15]
	s_waitcnt vmcnt(14)
	v_mfma_f32_32x32x16_bf16 v[16:31], v[238:241], v[146:149], v[16:31]
	s_waitcnt vmcnt(13)
	v_mfma_f32_32x32x16_bf16 v[32:47], v[242:245], v[146:149], v[32:47]
	s_waitcnt vmcnt(12)
	v_mfma_f32_32x32x16_bf16 v[48:63], v[246:249], v[146:149], v[48:63]
	s_waitcnt vmcnt(11)
	v_mfma_f32_32x32x16_bf16 v[0:15], v[76:79], v[150:153], v[0:15]
	s_waitcnt vmcnt(10)
	v_mfma_f32_32x32x16_bf16 v[16:31], v[80:83], v[150:153], v[16:31]
	s_waitcnt vmcnt(9)
	v_mfma_f32_32x32x16_bf16 v[32:47], v[84:87], v[150:153], v[32:47]
	s_waitcnt vmcnt(8)
	v_mfma_f32_32x32x16_bf16 v[48:63], v[88:91], v[150:153], v[48:63]
	s_waitcnt vmcnt(7)
	v_mfma_f32_32x32x16_bf16 v[0:15], v[92:95], v[154:157], v[0:15]
	s_waitcnt vmcnt(6)
	v_mfma_f32_32x32x16_bf16 v[16:31], v[96:99], v[154:157], v[16:31]
	s_waitcnt vmcnt(5)
	v_mfma_f32_32x32x16_bf16 v[32:47], v[100:103], v[154:157], v[32:47]
	s_waitcnt vmcnt(4)
	v_mfma_f32_32x32x16_bf16 v[48:63], v[104:107], v[154:157], v[48:63]
	s_waitcnt vmcnt(3)
	v_mfma_f32_32x32x16_bf16 v[0:15], v[108:111], v[158:161], v[0:15]
	s_waitcnt vmcnt(2)
	v_mfma_f32_32x32x16_bf16 v[16:31], v[112:115], v[158:161], v[16:31]
	s_waitcnt vmcnt(1)
	v_mfma_f32_32x32x16_bf16 v[32:47], v[116:119], v[158:161], v[32:47]
	s_waitcnt vmcnt(0)
	v_mfma_f32_32x32x16_bf16 v[48:63], v[120:123], v[158:161], v[48:63]
	v_add_u32_e32 v64, s14, v200
	v_ashrrev_i32_e32 v65, 31, v64
	v_readlane_b32 s14, v252, 41
	v_lshlrev_b64 v[64:65], 12, v[64:65]
	v_readlane_b32 s15, v252, 42
	s_nop 1
	v_lshl_add_u64 v[184:185], s[14:15], 0, v[64:65]
	s_branch .LBB0_2103

.LBB0_2103:
	v_writelane_b32 v255, s19, 57
	s_nop 0
	v_readlane_b32 s14, v255, 50
	s_add_i32 s22, s19, s14
	s_lshl_b32 s14, s22, 14
	v_readlane_b32 s15, v255, 51
	s_add_u32 s14, s15, s14
	v_readlane_b32 s15, v255, 54
	s_addc_u32 s15, s15, 0
	s_lshl_b64 s[16:17], s[22:23], 14
	v_readlane_b32 s19, v255, 55
	s_add_u32 s16, s19, s16
	v_readlane_b32 s19, v255, 56
	s_addc_u32 s17, s19, s17
	s_lshl_b64 s[20:21], s[22:23], 13
	v_readlane_b32 vcc_lo, v255, 52
	v_readlane_b32 vcc_hi, v255, 53
	s_add_u32 s20, s20, vcc_lo
	s_addc_u32 s21, s21, vcc_hi
	s_lshl_b64 s[20:21], s[20:21], 1
	s_or_b32 s19, s20, 0x80000
	v_readlane_b32 vcc_lo, v252, 49
	v_readlane_b32 vcc_hi, v252, 50
	s_add_u32 s20, vcc_lo, s19
	v_lshl_add_u64 v[64:65], s[14:15], 0, v[176:177]
	s_addc_u32 s21, vcc_hi, s21
	s_lshl_b32 s100, s22, 7
	s_add_u32 s100, s100, s12
	s_lshl_b32 s100, s100, 2
	s_mov_b32 s101, 0
	v_lshl_add_u64 v[222:223], s[100:101], 0, v[216:217]
	v_readlane_b32 s100, v255, 58
	v_readlane_b32 s101, v255, 59
	global_load_dwordx2 v[224:225], v[222:223], off
	global_load_dwordx4 v[64:67], v[64:65], off
	v_lshl_add_u64 v[68:69], s[16:17], 0, v[176:177]
	global_load_dwordx4 v[68:71], v[68:69], off
	v_lshl_add_u64 v[72:73], s[20:21], 0, v[176:177]
	global_load_dwordx4 v[72:75], v[72:73], off
	v_lshl_add_u64 v[76:77], s[14:15], 0, v[178:179]
	global_load_dwordx4 v[76:79], v[76:77], off
	v_lshl_add_u64 v[80:81], s[16:17], 0, v[178:179]
	global_load_dwordx4 v[80:83], v[80:81], off
	v_lshl_add_u64 v[84:85], s[20:21], 0, v[178:179]
	global_load_dwordx4 v[84:87], v[84:85], off
	v_lshl_add_u64 v[88:89], s[14:15], 0, v[180:181]
	global_load_dwordx4 v[88:91], v[88:89], off
	v_lshl_add_u64 v[92:93], s[16:17], 0, v[180:181]
	global_load_dwordx4 v[92:95], v[92:93], off
	v_lshl_add_u64 v[96:97], s[20:21], 0, v[180:181]
	global_load_dwordx4 v[96:99], v[96:97], off
	v_lshl_add_u64 v[100:101], s[14:15], 0, v[182:183]
	global_load_dwordx4 v[100:103], v[100:101], off
	v_lshl_add_u64 v[104:105], s[16:17], 0, v[182:183]
	global_load_dwordx4 v[104:107], v[104:105], off
	v_lshl_add_u64 v[108:109], s[20:21], 0, v[182:183]
	global_load_dwordx4 v[108:111], v[108:109], off
	v_writelane_b32 v252, s22, 12
	s_lshl_b32 s19, s22, 7
	s_mov_b64 s[14:15], -1
	v_writelane_b32 v252, s23, 13
	s_mov_b32 s20, 0
	s_barrier
	s_waitcnt vmcnt(11)
	ds_write_b64 v226, v[224:225]
	ds_write_b128 v201, v[64:67]
	s_waitcnt vmcnt(10)
	v_and_b32_e32 v68, s100, v68
	v_and_b32_e32 v69, s100, v69
	v_and_b32_e32 v70, s100, v70
	v_and_b32_e32 v71, s100, v71
	ds_write_b128 v201, v[68:71] offset:17408
	s_waitcnt vmcnt(9)
	v_and_b32_e32 v72, s101, v72
	v_and_b32_e32 v73, s101, v73
	v_and_b32_e32 v74, s101, v74
	v_and_b32_e32 v75, s101, v75
	ds_write_b128 v201, v[72:75] offset:34816
	s_waitcnt vmcnt(8)
	ds_write_b128 v202, v[76:79]
	s_waitcnt vmcnt(7)
	v_and_b32_e32 v80, s100, v80
	v_and_b32_e32 v81, s100, v81
	v_and_b32_e32 v82, s100, v82
	v_and_b32_e32 v83, s100, v83
	ds_write_b128 v202, v[80:83] offset:17408
	s_waitcnt vmcnt(6)
	v_and_b32_e32 v84, s101, v84
	v_and_b32_e32 v85, s101, v85
	v_and_b32_e32 v86, s101, v86
	v_and_b32_e32 v87, s101, v87
	ds_write_b128 v202, v[84:87] offset:34816
	s_waitcnt vmcnt(5)
	ds_write_b128 v203, v[88:91]
	s_waitcnt vmcnt(4)
	v_and_b32_e32 v92, s100, v92
	v_and_b32_e32 v93, s100, v93
	v_and_b32_e32 v94, s100, v94
	v_and_b32_e32 v95, s100, v95
	ds_write_b128 v203, v[92:95] offset:17408
	s_waitcnt vmcnt(3)
	v_and_b32_e32 v96, s101, v96
	v_and_b32_e32 v97, s101, v97
	v_and_b32_e32 v98, s101, v98
	v_and_b32_e32 v99, s101, v99
	ds_write_b128 v203, v[96:99] offset:34816
	s_waitcnt vmcnt(2)
	ds_write_b128 v204, v[100:103]
	s_waitcnt vmcnt(1)
	v_and_b32_e32 v104, s100, v104
	v_and_b32_e32 v105, s100, v105
	v_and_b32_e32 v106, s100, v106
	v_and_b32_e32 v107, s100, v107
	ds_write_b128 v204, v[104:107] offset:17408
	s_waitcnt vmcnt(0)
	v_and_b32_e32 v108, s101, v108
	v_and_b32_e32 v109, s101, v109
	v_and_b32_e32 v110, s101, v110
	v_and_b32_e32 v111, s101, v111
	ds_write_b128 v204, v[108:111] offset:34816
	v_mov_b32_e32 v78, v129
	v_mov_b32_e32 v79, v129
	v_mov_b32_e32 v64, v129
	v_mov_b32_e32 v65, v129
	v_mov_b32_e32 v66, v129
	v_mov_b32_e32 v67, v129
	v_mov_b32_e32 v68, v129
	v_mov_b32_e32 v69, v129
	v_mov_b32_e32 v70, v129
	v_mov_b32_e32 v71, v129
	v_mov_b32_e32 v72, v129
	v_mov_b32_e32 v73, v129
	v_mov_b32_e32 v74, v129
	v_mov_b32_e32 v75, v129
	v_mov_b32_e32 v76, v129
	v_mov_b32_e32 v77, v129
	v_mov_b64_e32 v[94:95], v[78:79]
	v_mov_b64_e32 v[92:93], v[76:77]
	v_mov_b64_e32 v[90:91], v[74:75]
	v_mov_b64_e32 v[88:89], v[72:73]
	v_mov_b64_e32 v[86:87], v[70:71]
	v_mov_b64_e32 v[84:85], v[68:69]
	v_mov_b64_e32 v[82:83], v[66:67]
	v_mov_b64_e32 v[80:81], v[64:65]
	s_waitcnt lgkmcnt(0)
	s_barrier
	s_branch .LBB0_2105
